# next-group input cast: next row's loads in flight while the current row is reduced/stored
# baseline (speedup 1.0000x reference)
; DI void phase_xcast(const float* x, bf16* H, float* slots, int bid, int nb, int tid) {
;     const int wave = tid >> 6, lane = tid & 63;
;     for (int row = bid * 8 + wave; row < MG; row += nb * 8) {
;         const float4* xr = (const float4*)(x + (size_t)row * DM); float4 v[4]; float ss = 0.f;
; #pragma unroll
;         for (int q = 0; q < 4; ++q) { v[q] = xr[lane + 64 * q]; ss += v[q].x * v[q].x + v[q].y * v[q].y + v[q].z * v[q].z + v[q].w * v[q].w; }
.LBB0_817:
	v_readlane_b32 s26, v255, 1
	v_readlane_b32 s27, v255, 2
	s_and_b64 s[0:1], s[88:89], s[26:27]
	s_andn2_b64 vcc, exec, s[0:1]
	s_movk_i32 s18, 0x3fff
	s_cbranch_vccnz .LBB0_824
	s_lshl_b32 s8, s86, 3
	v_ashrrev_i32_e32 v2, 6, v158
	v_add_u32_e32 v1, s8, v2
	s_movk_i32 s0, 0x4000
	v_cmp_gt_i32_e32 vcc, s0, v1
	s_and_saveexec_b64 s[4:5], vcc
	s_cbranch_execz .LBB0_823
	v_and_b32_e32 v3, 64, v216
	v_add_u32_e32 v3, 64, v3
	v_xor_b32_e32 v5, 32, v216
	v_cmp_lt_i32_e64 s[2:3], v5, v3
	s_waitcnt vmcnt(1)
	v_xor_b32_e32 v6, 16, v216
	s_ashr_i32 s9, s8, 31
	v_cndmask_b32_e64 v5, v216, v5, s[2:3]
	v_cmp_lt_i32_e64 s[2:3], v6, v3
	v_readlane_b32 s0, v252, 34
	v_readlane_b32 s1, v252, 35
	v_cndmask_b32_e64 v6, v216, v6, s[2:3]
	s_waitcnt vmcnt(0)
	v_lshlrev_b32_e32 v10, 2, v6
	v_xor_b32_e32 v6, 8, v216
	v_cmp_lt_i32_e64 s[2:3], v6, v3
	v_and_b32_e32 v15, 63, v158
	s_lshl_b32 s6, s87, 3
	v_cndmask_b32_e64 v6, v216, v6, s[2:3]
	v_lshlrev_b32_e32 v11, 2, v6
	v_xor_b32_e32 v6, 4, v216
	v_cmp_lt_i32_e64 s[2:3], v6, v3
	s_ashr_i32 s7, s6, 31
	v_cmp_eq_u32_e32 vcc, 0, v15
	v_cndmask_b32_e64 v6, v216, v6, s[2:3]
	v_lshlrev_b32_e32 v12, 2, v6
	v_xor_b32_e32 v6, 2, v216
	v_cmp_lt_i32_e64 s[2:3], v6, v3
	v_lshlrev_b32_e32 v5, 2, v5
	s_lshl_b64 s[10:11], s[6:7], 12
	v_cndmask_b32_e64 v6, v216, v6, s[2:3]
	v_lshlrev_b32_e32 v13, 2, v6
	v_xor_b32_e32 v6, 1, v216
	v_cmp_lt_i32_e64 s[2:3], v6, v3
	s_lshl_b64 s[12:13], s[6:7], 11
	s_mov_b64 s[14:15], 0
	v_cndmask_b32_e64 v3, v216, v6, s[2:3]
	v_lshlrev_b32_e32 v14, 2, v3
	v_ashrrev_i32_e32 v3, 31, v2
	v_lshl_add_u64 v[8:9], v[2:3], 0, s[8:9]
	v_lshl_add_u64 v[2:3], v[8:9], 4, s[0:1]
	s_waitcnt lgkmcnt(0)
	v_lshlrev_b64 v[6:7], 12, v[8:9]
	v_readlane_b32 s0, v254, 47
	v_lshl_or_b32 v6, v15, 4, v6
	v_readlane_b32 s1, v254, 48
	v_lshlrev_b64 v[8:9], 11, v[8:9]
	v_lshl_or_b32 v8, v15, 3, v8
	v_lshl_add_u64 v[6:7], s[0:1], 0, v[6:7]
	v_readlane_b32 s0, v253, 57
	v_readlane_b32 s1, v253, 58
	s_lshl_b64 s[8:9], s[6:7], 4
	s_nop 0
	v_lshl_add_u64 v[8:9], s[0:1], 0, v[8:9]
	global_load_dwordx4 v[48:51], v[6:7], off
	global_load_dwordx4 v[52:55], v[6:7], off offset:1024
	global_load_dwordx4 v[56:59], v[6:7], off offset:2048
	global_load_dwordx4 v[60:63], v[6:7], off offset:3072
	s_waitcnt vmcnt(0)
	s_branch .LBB0_821

; DI unsigned pk(float lo, float hi) { return pg8::cvt_pk_bf16(lo, hi); }
; DI void phase_xcast(const float* x, bf16* H, float* slots, int bid, int nb, int tid) {
;     ...
;     for (int row = bid * 8 + wave; row < MG; row += nb * 8) {
;         const float4* xr = (const float4*)(x + (size_t)row * DM); float4 v[4]; float ss = 0.f;
; #pragma unroll
;         for (int q = 0; q < 4; ++q) { v[q] = xr[lane + 64 * q]; ss += v[q].x * v[q].x + v[q].y * v[q].y + v[q].z * v[q].z + v[q].w * v[q].w; }
; #pragma unroll
;         for (int o = 32; o >= 1; o >>= 1) ss += __shfl_xor(ss, o);
; #pragma unroll
;         for (int q = 0; q < 4; ++q) { uint2 w; w.x = pk(v[q].x, v[q].y); w.y = pk(v[q].z, v[q].w); *(uint2*)(H + (size_t)row * DM + (lane + 64 * q) * 4) = w; }
;         if (lane == 0) *(float4*)(slots + (size_t)row * 4) = make_float4(ss, 0.f, 0.f, 0.f);
.LBB0_821:
	s_waitcnt lgkmcnt(0)
	s_waitcnt vmcnt(4)
	v_mov_b32_e32 v16, v48
	v_mov_b32_e32 v17, v49
	v_mov_b32_e32 v18, v50
	v_mov_b32_e32 v19, v51
	v_mov_b32_e32 v20, v52
	v_mov_b32_e32 v21, v53
	v_mov_b32_e32 v22, v54
	v_mov_b32_e32 v23, v55
	v_mov_b32_e32 v24, v56
	v_mov_b32_e32 v25, v57
	v_mov_b32_e32 v26, v58
	v_mov_b32_e32 v27, v59
	v_mov_b32_e32 v28, v60
	v_mov_b32_e32 v29, v61
	v_mov_b32_e32 v30, v62
	v_mov_b32_e32 v31, v63
	v_add_u32_e32 v64, s6, v1
	v_lshl_add_u64 v[66:67], v[6:7], 0, s[10:11]
	v_cmp_ge_i32_e64 s[98:99], s18, v64
	s_and_saveexec_b64 s[100:101], s[98:99]
	global_load_dwordx4 v[48:51], v[66:67], off
	global_load_dwordx4 v[52:55], v[66:67], off offset:1024
	global_load_dwordx4 v[56:59], v[66:67], off offset:2048
	global_load_dwordx4 v[60:63], v[66:67], off offset:3072
	s_mov_b64 exec, s[100:101]
	v_pk_mul_f32 v[32:33], v[16:17], v[16:17]
	v_pk_mul_f32 v[36:37], v[20:21], v[20:21]
	v_pk_mul_f32 v[34:35], v[18:19], v[18:19]
	v_pk_mul_f32 v[38:39], v[22:23], v[22:23]
	v_pk_mul_f32 v[40:41], v[24:25], v[24:25]
	v_add_f32_e32 v15, v36, v37
	v_add_f32_e32 v32, v32, v33
	v_pk_mul_f32 v[42:43], v[26:27], v[26:27]
	v_pk_mul_f32 v[44:45], v[28:29], v[28:29]
	v_add_f32_e32 v33, v40, v41
	v_add_f32_e32 v15, v15, v38
	v_add_f32_e32 v32, v32, v34
	v_pk_mul_f32 v[46:47], v[30:31], v[30:31]
	v_add_f32_e32 v36, v44, v45
	v_add_f32_e32 v33, v33, v42
	v_add_f32_e32 v15, v15, v39
	v_add_f32_e32 v32, v32, v35
	v_add_f32_e32 v34, v36, v46
	v_add_f32_e32 v33, v33, v43
	v_add_f32_e32 v15, v32, v15
	v_add_f32_e32 v34, v34, v47
	v_add_f32_e32 v15, v15, v33
	v_add_f32_e32 v15, v15, v34
	ds_bpermute_b32 v32, v5, v15
	v_cvt_pk_bf16_f32 v16, v16, v17
	v_cvt_pk_bf16_f32 v17, v18, v19
	v_cvt_pk_bf16_f32 v18, v20, v21
	v_cvt_pk_bf16_f32 v19, v22, v23
	s_waitcnt lgkmcnt(0)
	v_add_f32_e32 v15, v15, v32
	ds_bpermute_b32 v32, v10, v15
	global_store_dwordx2 v[8:9], v[16:17], off offset:-1024
	global_store_dwordx2 v[8:9], v[18:19], off offset:-512
	v_cvt_pk_bf16_f32 v20, v24, v25
	v_cvt_pk_bf16_f32 v18, v28, v29
	v_cvt_pk_bf16_f32 v19, v30, v31
	s_waitcnt lgkmcnt(0)
	v_add_f32_e32 v15, v15, v32
	ds_bpermute_b32 v32, v11, v15
	global_store_dwordx2 v[8:9], v[18:19], off offset:512
	s_waitcnt lgkmcnt(0)
	v_add_f32_e32 v15, v15, v32
	ds_bpermute_b32 v32, v12, v15
	s_waitcnt lgkmcnt(0)
	v_add_f32_e32 v15, v15, v32
	ds_bpermute_b32 v21, v13, v15
	s_waitcnt lgkmcnt(0)
	v_add_f32_e32 v15, v15, v21
	ds_bpermute_b32 v16, v14, v15
	v_cvt_pk_bf16_f32 v21, v26, v27
	global_store_dwordx2 v[8:9], v[20:21], off
	s_and_saveexec_b64 s[2:3], vcc
	s_cbranch_execz .LBB0_820
	s_waitcnt lgkmcnt(0)
	v_add_f32_e32 v16, v15, v16
	v_mov_b32_e32 v17, v0
	v_mov_b32_e32 v18, v0
	v_mov_b32_e32 v19, v0
	global_store_dwordx4 v[2:3], v[16:19], off
	s_branch .LBB0_820
